# mixers queue: latent Hyena items request the block's next ticket at item start (no atomic round trip / store drain at the loop top)
# baseline (speedup 1.0000x reference)
;   if (!(bid & 1)) for (int it = bid >> 1; it < 256; it += (nblk + 1) >> 1) ssd_item(p, l, it, smem);
;   const int nf = (l == 0) ? 288 : 256;
;   const int nh = (l == 0) ? 1280 : 1024;
;   int* ctr = WSP(int, OFF_CTR) + l + 2 * rep;
;   int* sitem = (int*)(smem + LDS_BYTES - 16);
;   for (;;) {
.LBB0_1125:
	s_setprio 0
	v_readlane_b32 s0, v254, 8
	v_readlane_b32 s1, v254, 9
	s_and_b64 s[0:1], s[0:1], exec
	s_movk_i32 s0, 0x120
	s_cselect_b32 s40, s0, 0x100
	s_mov_b32 s25, s87
	s_movk_i32 s0, 0x620
	s_cselect_b32 s41, s0, 0x500
	s_lshl_b32 s42, s24, 8
	s_lshl_b32 s86, s24, 13
	s_lshl_b64 s[0:1], s[24:25], 2
	v_readlane_b32 s13, v255, 48
	s_add_u32 s0, s13, s0
	v_readlane_b32 s13, v255, 49
	s_addc_u32 s1, s13, s1
	s_lshl_b64 s[34:35], s[86:87], 2
	v_readlane_b32 s16, v254, 45
	v_readlane_b32 s17, v254, 46
	s_add_u32 s43, s16, s34
	s_addc_u32 s44, s17, s35
	s_mov_b32 s64, s24
	s_mov_b32 s32, 0
	s_branch .LBB0_1129

; DI int TID() { int t = threadIdx.x; asm volatile("" : "+v"(t)); return t; }
;     ...
;     if (TID() == 0) *sitem = atomicAdd(ctr, 1);
.LBB0_1129:
	v_mov_b32_e32 v0, v218
	s_nop 0
	v_cmp_eq_u32_e32 vcc, 0, v0
	s_and_saveexec_b64 s[34:35], vcc
	s_cbranch_execz .LBB0_1133
	s_cmp_eq_u32 s32, 0
	s_cbranch_scc1 .Ltk_fetch
	s_mov_b32 s32, 0
	v_mov_b32_e32 v0, v120
	s_branch .Ltk_have
.Ltk_fetch:
	s_mov_b64 s[38:39], exec
	v_mbcnt_lo_u32_b32 v0, s38, 0
	v_mbcnt_hi_u32_b32 v0, s39, v0
	v_cmp_eq_u32_e32 vcc, 0, v0
	s_and_saveexec_b64 s[36:37], vcc
	s_cbranch_execz .LBB0_1132
	s_bcnt1_i32_b64 s13, s[38:39]
	v_mov_b32_e32 v1, s13
	global_atomic_add v1, v173, v1, s[0:1] sc0

; DI int TID() { int t = threadIdx.x; asm volatile("" : "+v"(t)); return t; }
;     ...
;     if (TID() == 0) *sitem = atomicAdd(ctr, 1);
.Ltk_have:
	v_readlane_b32 s13, v254, 1
	s_nop 1
	v_mov_b32_e32 v1, s13
	ds_write_b32 v1, v0

; DI void hyena_item_lat(const Params& p, int l, int it) {
;     ...
;   const int c = it >> 2, f = l, L = 2048, posoff = CTXL;
;   const int tt0 = (it & 3) * 512 + w * 128;
;   const u16* R0 = WSP(const u16, OFF_RF) + ((size_t)(f * 256 + c) * 2) * RSTR;
;   const u16* R1 = R0 + RSTR;
;   const u16* UT = WSP(const u16, OFF_UT);
;   const int l16 = lane & 15, kg = lane >> 4;
;   f32x4 acc[8];
; #pragma unroll
;   for (int i = 0; i < 8; ++i) acc[i] = (f32x4){0.f, 0.f, 0.f, 0.f};
;   const u16* ub = UT + ((size_t)(c * 16 + l16)) * TPB + posoff + kg * 8;
;   const u16* rsel = (l16 & 1) ? (R1 - 1) : R0;
;   const int nb = L - (tt0 + l16) + kg * 8;
;   union AF { u32 u[4]; bf16x8 v; };
;   AF a[8];
;     ...
; #pragma unroll
;   for (int i = 2; i < 8; ++i) HY_LOADA(a[i], nb - 16 * i)
.LBB0_1137:
	s_andn2_b64 vcc, exec, s[34:35]
	s_cbranch_vccnz .LBB0_1141
	v_cmp_eq_u32_e64 s[38:39], 0, v218
	s_and_saveexec_b64 s[36:37], s[38:39]
	v_mov_b32_e32 v120, 1
	global_atomic_add v120, v173, v120, s[0:1] sc0
	s_mov_b64 exec, s[36:37]
	s_mov_b32 s32, 1
	s_ashr_i32 s34, s13, 2
	v_mov_b32_e32 v0, v218
	v_mov_b32_e32 v1, v218
	s_add_i32 s36, s34, s42
	s_lshl_b32 s13, s13, 9
	s_ashr_i32 s37, s36, 31
	s_mul_i32 s38, s36, 0x4040
	v_readlane_b32 s16, v254, 47
	v_lshlrev_b32_e32 v1, 1, v1
	s_mul_hi_i32 s35, s36, 0x4040
	v_readlane_b32 s17, v254, 48
	s_add_u32 s38, s16, s38
	v_and_b32_e32 v1, 0xffffff80, v1
	s_addc_u32 s39, s17, s35
	s_and_b32 s13, s13, 0x600
	v_add_u32_e32 v63, s13, v1
	v_and_b32_e32 v62, 15, v0
	v_bfe_u32 v64, v0, 4, 2
	v_bfe_i32 v0, v0, 0, 1
	v_lshlrev_b32_e32 v1, 3, v64
	v_and_b32_e32 v172, 0x201e, v0
	v_or_b32_e32 v0, v63, v62
	v_sub_u32_e32 v58, v1, v0
	v_lshl_add_u64 v[56:57], s[38:39], 0, v[172:173]
	v_ashrrev_i32_e32 v59, 31, v58
	v_lshl_add_u64 v[0:1], v[58:59], 1, v[56:57]
	global_load_dwordx4 v[40:43], v[0:1], off offset:4032
	global_load_dwordx4 v[44:47], v[0:1], off offset:4000
	global_load_dwordx4 v[32:35], v[0:1], off offset:3968
	global_load_dwordx4 v[36:39], v[0:1], off offset:3936
	global_load_dwordx4 v[48:51], v[0:1], off offset:3904
	global_load_dwordx4 v[52:55], v[0:1], off offset:3872
	s_lshl_b32 s35, s34, 4
	v_or_b32_e32 v59, s35, v62
	v_mad_i64_i32 v[0:1], s[38:39], v59, s9, 0
	v_readlane_b32 s16, v255, 56
	v_lshl_or_b32 v0, v64, 4, v0
	v_readlane_b32 s17, v255, 57
	v_mov_b32_e32 v28, 0
	s_mov_b64 s[46:47], s[20:21]
	s_movk_i32 s13, 0xff80
	v_lshl_add_u64 v[60:61], s[16:17], 0, v[0:1]
	v_mov_b32_e32 v29, v28
	v_mov_b32_e32 v30, v28
	v_mov_b32_e32 v31, v28
	v_mov_b32_e32 v24, v28
	v_mov_b32_e32 v25, v28
	v_mov_b32_e32 v26, v28
	v_mov_b32_e32 v27, v28
	v_mov_b32_e32 v20, v28
	v_mov_b32_e32 v21, v28
	v_mov_b32_e32 v22, v28
	v_mov_b32_e32 v23, v28
	v_mov_b32_e32 v16, v28
	v_mov_b32_e32 v17, v28
	v_mov_b32_e32 v18, v28
	v_mov_b32_e32 v19, v28
	v_mov_b32_e32 v12, v28
	v_mov_b32_e32 v13, v28
	v_mov_b32_e32 v14, v28
	v_mov_b32_e32 v15, v28
	v_mov_b32_e32 v8, v28
	v_mov_b32_e32 v9, v28
	v_mov_b32_e32 v10, v28
	v_mov_b32_e32 v11, v28
	v_mov_b32_e32 v4, v28
	v_mov_b32_e32 v5, v28
	v_mov_b32_e32 v6, v28
	v_mov_b32_e32 v7, v28
	v_mov_b32_e32 v0, v28
	v_mov_b32_e32 v1, v28
	v_mov_b32_e32 v2, v28
	v_mov_b32_e32 v3, v28
	v_and_b32_e32 v92, 0xc0, v218
	v_mov_b32_e32 v93, 0
	v_lshlrev_b32_e32 v94, 4, v218
	v_and_b32_e32 v95, 63, v218
	v_lshl_add_u64 v[90:91], v[92:93], 0, v[60:61]
	v_lshlrev_b32_e32 v95, 4, v95
	global_load_dwordx4 v[82:85], v[90:91], off offset:-192
